# attention epilogue: gate loads issued at epilogue start (hidden behind the LDS exchange)
# speedup vs baseline: 1.0071x; 1.0025x over previous
.LBB0_295:
	s_cmp_gt_u32 s69, 3
	s_cbranch_scc1 .Laepi_skip
	v_lshl_or_b32 v144, v198, 6, s67
	v_mov_b32_e32 v145, v187
	v_or_b32_e32 v144, v144, v186
	v_lshlrev_b64 v[144:145], 1, v[144:145]
	v_lshl_add_u64 v[144:145], s[18:19], 0, v[144:145]
	global_load_dwordx4 v[146:149], v[144:145], off
	global_load_dwordx4 v[150:153], v[144:145], off offset:16
	global_load_dwordx4 v[154:157], v[144:145], off offset:32
	global_load_dwordx4 v[158:161], v[144:145], off offset:48
	global_load_dwordx4 v[162:165], v[144:145], off offset:64
	global_load_dwordx4 v[166:169], v[144:145], off offset:80
	global_load_dwordx4 v[170:173], v[144:145], off offset:96
	global_load_dwordx4 v[174:177], v[144:145], off offset:112

.LBB0_299:
	s_andn2_b64 vcc, exec, s[0:1]
	s_waitcnt lgkmcnt(0)
	s_barrier
	s_cbranch_vccnz .LBB0_266
	ds_read2_b32 v[84:85], v82 offset1:32
	ds_read2_b32 v[86:87], v82 offset0:132 offset1:164
	v_add_u32_e32 v102, 0x1000, v82
	ds_read2_b32 v[90:91], v102 offset0:164 offset1:196
	v_add_u32_e32 v103, 0x1400, v82
	s_waitcnt lgkmcnt(2)
	v_fma_f32 v83, v50, v66, -v84
	s_waitcnt lgkmcnt(1)
	v_fma_f32 v84, v51, v70, -v86
	v_add_u32_e32 v86, 0x400, v82
	ds_read2_b32 v[50:51], v86 offset0:8 offset1:40
	ds_read2_b32 v[88:89], v86 offset0:140 offset1:172
	s_waitcnt lgkmcnt(2)
	v_fma_f32 v90, v55, v73, -v90
	ds_read2_b32 v[92:93], v103 offset0:172 offset1:204
	v_add_u32_e32 v104, 0x2000, v82
	s_waitcnt lgkmcnt(2)
	v_fma_f32 v50, v52, v69, -v50
	s_waitcnt lgkmcnt(1)
	v_fma_f32 v88, v53, v68, -v88
	ds_read2_b32 v[52:53], v102 offset0:32 offset1:64
	s_waitcnt lgkmcnt(1)
	v_fma_f32 v92, v57, v71, -v92
	ds_read2_b32 v[94:95], v104 offset0:196 offset1:228
	v_add_u32_e32 v105, 0x2400, v82
	ds_read2_b32 v[96:97], v105 offset0:204 offset1:236
	s_waitcnt lgkmcnt(2)
	v_fma_f32 v52, v54, v67, -v52
	ds_read2_b32 v[54:55], v103 offset0:40 offset1:72
	s_waitcnt lgkmcnt(2)
	v_fma_f32 v94, v59, v76, -v94
	v_add_u32_e32 v106, 0x3000, v82
	v_add_u32_e32 v107, 0x3200, v82
	s_waitcnt lgkmcnt(1)
	v_fma_f32 v96, v61, v74, -v96
	s_waitcnt lgkmcnt(0)
	v_fma_f32 v54, v56, v72, -v54
	ds_read2_b32 v[56:57], v104 offset0:64 offset1:96
	ds_read2_b32 v[98:99], v107 offset0:100 offset1:132
	v_fma_f32 v34, v34, v66, -v85
	ds_write2_b32 v82, v83, v34 offset1:32
	v_fma_f32 v34, v35, v70, -v87
	s_waitcnt lgkmcnt(2)
	v_fma_f32 v56, v58, v77, -v56
	ds_read2_b32 v[58:59], v105 offset0:72 offset1:104
	ds_write2_b32 v82, v84, v34 offset0:132 offset1:164
	v_fma_f32 v34, v36, v69, -v51
	v_add_u32_e32 v108, 0x3400, v82
	ds_write2_b32 v86, v50, v34 offset0:8 offset1:40
	s_waitcnt lgkmcnt(2)
	v_fma_f32 v58, v60, v75, -v58
	ds_read2_b32 v[60:61], v106 offset0:96 offset1:128
	v_fma_f32 v34, v37, v68, -v89
	v_fma_f32 v98, v63, v80, -v98
	ds_write2_b32 v86, v88, v34 offset0:140 offset1:172
	v_fma_f32 v34, v38, v67, -v53
	s_waitcnt lgkmcnt(1)
	v_fma_f32 v60, v62, v81, -v60
	ds_read2_b32 v[62:63], v108 offset0:104 offset1:136
	ds_write2_b32 v102, v52, v34 offset0:32 offset1:64
	v_fma_f32 v34, v39, v73, -v91
	ds_write2_b32 v102, v90, v34 offset0:164 offset1:196
	v_fma_f32 v34, v40, v72, -v55
	ds_write2_b32 v103, v54, v34 offset0:40 offset1:72
	v_fma_f32 v34, v41, v71, -v93
	ds_write2_b32 v103, v92, v34 offset0:172 offset1:204
	v_fma_f32 v34, v42, v77, -v57
	s_waitcnt lgkmcnt(4)
	v_fma_f32 v62, v64, v79, -v62
	v_add_u32_e32 v64, 0x3600, v82
	ds_write2_b32 v104, v56, v34 offset0:64 offset1:96
	v_fma_f32 v34, v43, v76, -v95
	ds_read2_b32 v[100:101], v64 offset0:108 offset1:140
	ds_write2_b32 v104, v94, v34 offset0:196 offset1:228
	v_fma_f32 v34, v44, v75, -v59
	ds_write2_b32 v105, v58, v34 offset0:72 offset1:104
	v_fma_f32 v34, v45, v74, -v97
	ds_write2_b32 v105, v96, v34 offset0:204 offset1:236
	v_fma_f32 v34, v46, v81, -v61
	ds_write2_b32 v106, v60, v34 offset0:96 offset1:128
	v_fma_f32 v34, v47, v80, -v99
	ds_write2_b32 v107, v98, v34 offset0:100 offset1:132
	v_fma_f32 v34, v48, v79, -v63
	s_waitcnt lgkmcnt(5)
	v_fma_f32 v65, v65, v78, -v100
	ds_write2_b32 v108, v62, v34 offset0:104 offset1:136
	v_fma_f32 v34, v49, v78, -v101
	ds_write2_b32 v64, v65, v34 offset0:108 offset1:140
	ds_read2_b32 v[34:35], v82 offset0:64 offset1:96
	ds_read2_b32 v[36:37], v82 offset0:196 offset1:228
	ds_read2_b32 v[38:39], v86 offset0:204 offset1:236
	v_add_u32_e32 v52, 0x1200, v82
	ds_read2_b32 v[40:41], v52 offset0:100 offset1:132
	s_waitcnt lgkmcnt(3)
	v_fma_f32 v34, v18, v66, -v34
	s_waitcnt lgkmcnt(2)
	v_fma_f32 v36, v19, v70, -v36
	ds_read2_b32 v[18:19], v86 offset0:72 offset1:104
	s_waitcnt lgkmcnt(2)
	v_fma_f32 v38, v21, v68, -v38
	v_add_u32_e32 v53, 0x1600, v82
	s_waitcnt lgkmcnt(1)
	v_fma_f32 v40, v23, v73, -v40
	ds_read2_b32 v[42:43], v53 offset0:108 offset1:140
	s_waitcnt lgkmcnt(1)
	v_fma_f32 v18, v20, v69, -v18
	ds_read2_b32 v[20:21], v102 offset0:96 offset1:128
	ds_read2_b32 v[44:45], v105 offset0:4 offset1:36
	v_add_u32_e32 v54, 0x2800, v82
	s_waitcnt lgkmcnt(2)
	v_fma_f32 v42, v25, v71, -v42
	ds_read2_b32 v[46:47], v54 offset0:12 offset1:44
	s_waitcnt lgkmcnt(2)
	v_fma_f32 v20, v22, v67, -v20
	ds_read2_b32 v[22:23], v103 offset0:104 offset1:136
	s_waitcnt lgkmcnt(2)
	v_fma_f32 v44, v27, v76, -v44
	ds_read2_b32 v[48:49], v108 offset0:36 offset1:68
	s_waitcnt lgkmcnt(2)
	v_fma_f32 v46, v29, v74, -v46
	v_fma_f32 v2, v2, v66, -v35
	s_waitcnt lgkmcnt(1)
	v_fma_f32 v22, v24, v72, -v22
	ds_read2_b32 v[24:25], v104 offset0:128 offset1:160
	ds_write2_b32 v82, v34, v2 offset0:64 offset1:96
	v_fma_f32 v2, v3, v70, -v37
	ds_write2_b32 v82, v36, v2 offset0:196 offset1:228
	v_fma_f32 v2, v4, v69, -v19
	s_waitcnt lgkmcnt(2)
	v_fma_f32 v24, v26, v77, -v24
	ds_read2_b32 v[26:27], v105 offset0:136 offset1:168
	ds_write2_b32 v86, v18, v2 offset0:72 offset1:104
	v_fma_f32 v2, v5, v68, -v39
	v_fma_f32 v48, v31, v80, -v48
	ds_write2_b32 v86, v38, v2 offset0:204 offset1:236
	s_waitcnt lgkmcnt(2)
	v_fma_f32 v26, v28, v75, -v26
	ds_read2_b32 v[28:29], v106 offset0:160 offset1:192
	v_fma_f32 v2, v6, v67, -v21
	ds_write2_b32 v102, v20, v2 offset0:96 offset1:128
	v_fma_f32 v2, v7, v73, -v41
	ds_write2_b32 v52, v40, v2 offset0:100 offset1:132
	s_waitcnt lgkmcnt(2)
	v_fma_f32 v28, v30, v81, -v28
	ds_read2_b32 v[30:31], v108 offset0:168 offset1:200
	v_fma_f32 v2, v8, v72, -v23
	ds_write2_b32 v103, v22, v2 offset0:104 offset1:136
	v_fma_f32 v2, v9, v71, -v43
	ds_write2_b32 v53, v42, v2 offset0:108 offset1:140
	v_fma_f32 v2, v10, v77, -v25
	s_waitcnt lgkmcnt(2)
	v_fma_f32 v30, v32, v79, -v30
	v_add_u32_e32 v32, 0x3800, v82
	ds_write2_b32 v104, v24, v2 offset0:128 offset1:160
	v_fma_f32 v2, v11, v76, -v45
	ds_read2_b32 v[50:51], v32 offset0:44 offset1:76
	ds_write2_b32 v105, v44, v2 offset0:4 offset1:36
	v_fma_f32 v2, v12, v75, -v27
	ds_write2_b32 v105, v26, v2 offset0:136 offset1:168
	v_fma_f32 v2, v13, v74, -v47
	ds_write2_b32 v54, v46, v2 offset0:12 offset1:44
	v_fma_f32 v2, v14, v81, -v29
	ds_write2_b32 v106, v28, v2 offset0:160 offset1:192
	v_fma_f32 v2, v15, v80, -v49
	ds_write2_b32 v108, v48, v2 offset0:36 offset1:68
	v_fma_f32 v2, v16, v79, -v31
	s_waitcnt lgkmcnt(5)
	v_fma_f32 v33, v33, v78, -v50
	ds_write2_b32 v108, v30, v2 offset0:168 offset1:200
	v_fma_f32 v2, v17, v78, -v51
	ds_write2_b32 v32, v33, v2 offset0:44 offset1:76
	v_mul_u32_u24_e32 v2, 0x210, v199
	v_lshlrev_b32_e32 v82, 8, v198
	s_waitcnt lgkmcnt(0)
	v_add3_u32 v71, s14, v2, v82
	ds_read_b128 v[50:53], v71
	ds_read_b128 v[46:49], v71 offset:16
	ds_read_b128 v[26:29], v71 offset:32
	ds_read_b128 v[18:21], v71 offset:48
	ds_read_b128 v[30:33], v71 offset:64
	s_waitcnt lgkmcnt(4)
	v_pk_mul_f32 v[2:3], v[52:53], v[52:53]
	v_pk_mul_f32 v[4:5], v[50:51], v[50:51]
	ds_read_b128 v[42:45], v71 offset:80
	v_pk_mov_b32 v[6:7], v[4:5], v[2:3] op_sel:[1,0]
	v_mov_b32_e32 v5, v3
	v_pk_add_f32 v[2:3], v[6:7], v[4:5]
	s_waitcnt lgkmcnt(4)
	v_pk_mul_f32 v[4:5], v[48:49], v[48:49]
	v_pk_mul_f32 v[6:7], v[46:47], v[46:47]
	v_pk_add_f32 v[2:3], v[2:3], v[2:3] op_sel:[0,1] op_sel_hi:[1,0]
	v_pk_mov_b32 v[8:9], v[6:7], v[4:5] op_sel:[1,0]
	v_mov_b32_e32 v7, v5
	v_pk_add_f32 v[4:5], v[8:9], v[6:7]
	s_waitcnt lgkmcnt(3)
	v_pk_mul_f32 v[6:7], v[28:29], v[28:29]
	v_pk_add_f32 v[4:5], v[4:5], v[4:5] op_sel:[0,1] op_sel_hi:[1,0]
	v_pk_mul_f32 v[8:9], v[26:27], v[26:27]
	s_waitcnt lgkmcnt(2)
	v_pk_mul_f32 v[10:11], v[20:21], v[20:21]
	v_pk_mul_f32 v[12:13], v[18:19], v[18:19]
	v_add_f32_e32 v8, v8, v9
	v_add_f32_e32 v6, v6, v7
	v_mov_b32_e32 v3, v12
	v_mov_b32_e32 v5, v13
	v_mov_b32_e32 v9, v10
	v_mov_b32_e32 v7, v11
	ds_read_b128 v[38:41], v71 offset:96
	v_pk_add_f32 v[2:3], v[2:3], v[4:5]
	v_pk_add_f32 v[4:5], v[8:9], v[6:7]
	s_waitcnt lgkmcnt(2)
	v_pk_mul_f32 v[6:7], v[30:31], v[30:31]
	v_pk_add_f32 v[2:3], v[2:3], v[4:5]
	v_pk_mul_f32 v[4:5], v[32:33], v[32:33]
	ds_read_b128 v[54:57], v71 offset:112
	v_pk_mov_b32 v[8:9], v[6:7], v[4:5] op_sel:[1,0]
	v_mov_b32_e32 v7, v5
	v_pk_add_f32 v[4:5], v[8:9], v[6:7]
	v_pk_add_f32 v[2:3], v[2:3], v[2:3] op_sel:[0,1] op_sel_hi:[1,0]
	v_pk_add_f32 v[4:5], v[4:5], v[4:5] op_sel:[0,1] op_sel_hi:[1,0]
	s_waitcnt lgkmcnt(2)
	v_pk_mul_f32 v[6:7], v[44:45], v[44:45]
	v_pk_mul_f32 v[8:9], v[42:43], v[42:43]
	s_waitcnt lgkmcnt(1)
	v_pk_mul_f32 v[10:11], v[40:41], v[40:41]
	v_pk_mul_f32 v[12:13], v[38:39], v[38:39]
	v_add_f32_e32 v8, v8, v9
	v_add_f32_e32 v6, v6, v7
	v_mov_b32_e32 v3, v12
	v_mov_b32_e32 v5, v13
	v_mov_b32_e32 v9, v10
	v_mov_b32_e32 v7, v11
	ds_read_b128 v[58:61], v71 offset:128
	ds_read_b128 v[62:65], v71 offset:144
	v_pk_add_f32 v[2:3], v[2:3], v[4:5]
	v_pk_add_f32 v[4:5], v[8:9], v[6:7]
	s_waitcnt lgkmcnt(2)
	v_pk_mul_f32 v[6:7], v[54:55], v[54:55]
	v_pk_add_f32 v[2:3], v[2:3], v[4:5]
	v_pk_mul_f32 v[4:5], v[56:57], v[56:57]
	ds_read_b128 v[34:37], v71 offset:160
	v_pk_mov_b32 v[8:9], v[6:7], v[4:5] op_sel:[1,0]
	v_mov_b32_e32 v7, v5
	v_pk_add_f32 v[4:5], v[8:9], v[6:7]
	v_pk_add_f32 v[2:3], v[2:3], v[2:3] op_sel:[0,1] op_sel_hi:[1,0]
	v_pk_add_f32 v[4:5], v[4:5], v[4:5] op_sel:[0,1] op_sel_hi:[1,0]
	s_waitcnt lgkmcnt(2)
	v_pk_mul_f32 v[6:7], v[60:61], v[60:61]
	v_pk_mul_f32 v[8:9], v[58:59], v[58:59]
	s_waitcnt lgkmcnt(1)
	v_pk_mul_f32 v[10:11], v[64:65], v[64:65]
	v_pk_mul_f32 v[12:13], v[62:63], v[62:63]
	v_add_f32_e32 v8, v8, v9
	v_add_f32_e32 v6, v6, v7
	v_mov_b32_e32 v3, v12
	v_mov_b32_e32 v5, v13
	v_mov_b32_e32 v9, v10
	v_mov_b32_e32 v7, v11
	ds_read_b128 v[22:25], v71 offset:176
	ds_read_b128 v[14:17], v71 offset:192
	v_pk_add_f32 v[2:3], v[2:3], v[4:5]
	v_pk_add_f32 v[4:5], v[8:9], v[6:7]
	s_waitcnt lgkmcnt(2)
	v_pk_mul_f32 v[6:7], v[34:35], v[34:35]
	v_pk_add_f32 v[2:3], v[2:3], v[4:5]
	v_pk_mul_f32 v[4:5], v[36:37], v[36:37]
	v_pk_add_f32 v[2:3], v[2:3], v[2:3] op_sel:[0,1] op_sel_hi:[1,0]
	v_pk_mov_b32 v[8:9], v[6:7], v[4:5] op_sel:[1,0]
	v_mov_b32_e32 v7, v5
	v_pk_add_f32 v[4:5], v[8:9], v[6:7]
	s_waitcnt lgkmcnt(1)
	v_pk_mul_f32 v[6:7], v[24:25], v[24:25]
	v_pk_add_f32 v[4:5], v[4:5], v[4:5] op_sel:[0,1] op_sel_hi:[1,0]
	v_pk_mul_f32 v[8:9], v[22:23], v[22:23]
	s_waitcnt lgkmcnt(0)
	v_pk_mul_f32 v[10:11], v[16:17], v[16:17]
	v_pk_mul_f32 v[12:13], v[14:15], v[14:15]
	v_add_f32_e32 v8, v8, v9
	v_add_f32_e32 v6, v6, v7
	v_mov_b32_e32 v3, v12
	v_mov_b32_e32 v5, v13
	v_mov_b32_e32 v9, v10
	v_mov_b32_e32 v7, v11
	ds_read_b128 v[10:13], v71 offset:208
	v_pk_add_f32 v[2:3], v[2:3], v[4:5]
	v_pk_add_f32 v[4:5], v[8:9], v[6:7]
	s_nop 0
	v_pk_add_f32 v[2:3], v[2:3], v[4:5]
	s_waitcnt lgkmcnt(0)
	v_pk_mul_f32 v[4:5], v[10:11], v[10:11]
	v_pk_add_f32 v[66:67], v[2:3], v[2:3] op_sel:[0,1] op_sel_hi:[1,0]
	v_pk_mul_f32 v[2:3], v[12:13], v[12:13]
	s_nop 0
	v_pk_mov_b32 v[6:7], v[4:5], v[2:3] op_sel:[1,0]
	v_mov_b32_e32 v5, v3
	v_pk_add_f32 v[2:3], v[6:7], v[4:5]
	ds_read_b128 v[6:9], v71 offset:224
	v_pk_add_f32 v[68:69], v[2:3], v[2:3] op_sel:[0,1] op_sel_hi:[1,0]
	s_waitcnt lgkmcnt(0)
	v_pk_mul_f32 v[2:3], v[8:9], v[8:9]
	v_pk_mul_f32 v[4:5], v[6:7], v[6:7]
	v_add_f32_e32 v72, v2, v3
	v_add_f32_e32 v70, v4, v5
	ds_read_b128 v[2:5], v71 offset:240
	s_waitcnt lgkmcnt(0)
	v_pk_mul_f32 v[74:75], v[4:5], v[4:5]
	v_pk_mul_f32 v[76:77], v[2:3], v[2:3]
	v_mov_b32_e32 v71, v74
	v_mov_b32_e32 v67, v76
	v_mov_b32_e32 v69, v77
	v_mov_b32_e32 v73, v75
	v_pk_add_f32 v[66:67], v[66:67], v[68:69]
	v_pk_add_f32 v[68:69], v[70:71], v[72:73]
	s_nop 0
	v_pk_add_f32 v[66:67], v[66:67], v[68:69]
	s_nop 0
	v_add_f32_e32 v66, v66, v67
	ds_bpermute_b32 v0, v0, v66
	s_waitcnt lgkmcnt(0)
	v_add_f32_e32 v0, v66, v0
	v_lshl_or_b32 v66, v198, 6, s67
	v_or_b32_e32 v186, v66, v186
	v_lshlrev_b64 v[66:67], 1, v[186:187]
	v_lshl_add_u64 v[80:81], s[18:19], 0, v[66:67]
	v_lshl_add_u64 v[78:79], s[16:17], 0, v[66:67]
	global_load_dwordx4 v[98:101], v82, s[42:43]
	global_load_dwordx4 v[102:105], v82, s[42:43] offset:16
	global_load_dwordx4 v[106:109], v82, s[42:43] offset:32
	global_load_dwordx4 v[110:113], v82, s[42:43] offset:48
	global_load_dwordx4 v[114:117], v82, s[42:43] offset:64
	global_load_dwordx4 v[118:121], v82, s[42:43] offset:80
	global_load_dwordx4 v[122:125], v82, s[42:43] offset:96
	global_load_dwordx4 v[126:129], v82, s[42:43] offset:112
	global_load_dwordx4 v[130:133], v82, s[42:43] offset:128
	global_load_dwordx4 v[134:137], v82, s[42:43] offset:144
	global_load_dwordx4 v[138:141], v82, s[42:43] offset:160
	global_load_dwordx4 v[142:145], v82, s[42:43] offset:176
	global_load_dwordx4 v[66:69], v82, s[42:43] offset:192
	global_load_dwordx4 v[70:73], v82, s[42:43] offset:208
	global_load_dwordx4 v[74:77], v82, s[42:43] offset:224
	global_load_dwordx4 v[84:87], v82, s[42:43] offset:240
	v_fmamk_f32 v0, v0, 0x3c000000, v211
	v_rsq_f32_e32 v0, v0
	s_nop 0
	v_mul_f32_e32 v0, v197, v0
	v_pk_mul_f32 v[50:51], v[50:51], v[0:1] op_sel_hi:[1,0]
	v_pk_mul_f32 v[46:47], v[46:47], v[0:1] op_sel_hi:[1,0]
	v_pk_mul_f32 v[48:49], v[48:49], v[0:1] op_sel_hi:[1,0]
	v_pk_mul_f32 v[52:53], v[52:53], v[0:1] op_sel_hi:[1,0]
	v_pk_mul_f32 v[26:27], v[26:27], v[0:1] op_sel_hi:[1,0]
	v_pk_mul_f32 v[18:19], v[18:19], v[0:1] op_sel_hi:[1,0]
	v_pk_mul_f32 v[20:21], v[20:21], v[0:1] op_sel_hi:[1,0]
	v_pk_mul_f32 v[28:29], v[28:29], v[0:1] op_sel_hi:[1,0]
	v_pk_mul_f32 v[30:31], v[30:31], v[0:1] op_sel_hi:[1,0]
	v_pk_mul_f32 v[42:43], v[42:43], v[0:1] op_sel_hi:[1,0]
	v_pk_mul_f32 v[32:33], v[32:33], v[0:1] op_sel_hi:[1,0]
	v_pk_mul_f32 v[44:45], v[44:45], v[0:1] op_sel_hi:[1,0]
	v_pk_mul_f32 v[38:39], v[38:39], v[0:1] op_sel_hi:[1,0]
	v_pk_mul_f32 v[40:41], v[40:41], v[0:1] op_sel_hi:[1,0]
	v_pk_mul_f32 v[34:35], v[34:35], v[0:1] op_sel_hi:[1,0]
	v_pk_mul_f32 v[22:23], v[22:23], v[0:1] op_sel_hi:[1,0]
	v_pk_mul_f32 v[36:37], v[36:37], v[0:1] op_sel_hi:[1,0]
	v_pk_mul_f32 v[24:25], v[24:25], v[0:1] op_sel_hi:[1,0]
	v_pk_mul_f32 v[14:15], v[14:15], v[0:1] op_sel_hi:[1,0]
	v_pk_mul_f32 v[10:11], v[10:11], v[0:1] op_sel_hi:[1,0]
	v_pk_mul_f32 v[12:13], v[12:13], v[0:1] op_sel_hi:[1,0]
	v_pk_mul_f32 v[16:17], v[16:17], v[0:1] op_sel_hi:[1,0]
	v_pk_mul_f32 v[6:7], v[6:7], v[0:1] op_sel_hi:[1,0]
	v_pk_mul_f32 v[2:3], v[2:3], v[0:1] op_sel_hi:[1,0]
	v_pk_mul_f32 v[4:5], v[4:5], v[0:1] op_sel_hi:[1,0]
	v_pk_mul_f32 v[8:9], v[8:9], v[0:1] op_sel_hi:[1,0]
	v_pk_mul_f32 v[54:55], v[54:55], v[0:1] op_sel_hi:[1,0]
	v_pk_mul_f32 v[56:57], v[56:57], v[0:1] op_sel_hi:[1,0]
	v_pk_mul_f32 v[58:59], v[58:59], v[0:1] op_sel_hi:[1,0]
	v_pk_mul_f32 v[60:61], v[60:61], v[0:1] op_sel_hi:[1,0]
	v_pk_mul_f32 v[62:63], v[62:63], v[0:1] op_sel_hi:[1,0]
	v_pk_mul_f32 v[64:65], v[64:65], v[0:1] op_sel_hi:[1,0]
	s_waitcnt vmcnt(14)
	v_pk_mul_f32 v[50:51], v[98:99], v[50:51]
	v_pk_mul_f32 v[52:53], v[100:101], v[52:53]
	v_pk_mul_f32 v[46:47], v[102:103], v[46:47]
	v_pk_mul_f32 v[48:49], v[104:105], v[48:49]
	v_lshlrev_b32_e32 v88, 16, v146
	v_and_b32_e32 v146, 0xffff0000, v146
	v_lshlrev_b32_e32 v89, 16, v147
	v_and_b32_e32 v147, 0xffff0000, v147
	v_lshlrev_b32_e32 v90, 16, v148
	v_and_b32_e32 v148, 0xffff0000, v148
	v_lshlrev_b32_e32 v91, 16, v149
	v_and_b32_e32 v149, 0xffff0000, v149
	v_mul_f32_e32 v88, v50, v88
	v_mul_f32_e32 v146, v51, v146
	v_mul_f32_e32 v89, v52, v89
	v_mul_f32_e32 v147, v53, v147
	v_mul_f32_e32 v90, v46, v90
	v_mul_f32_e32 v148, v47, v148
	v_mul_f32_e32 v91, v48, v91
	v_mul_f32_e32 v149, v49, v149
	v_cvt_pk_bf16_f32 v146, v88, v146
	v_cvt_pk_bf16_f32 v147, v89, v147
	v_cvt_pk_bf16_f32 v148, v90, v148
	v_cvt_pk_bf16_f32 v149, v91, v149
	global_store_dwordx4 v[78:79], v[146:149], off
	s_waitcnt vmcnt(13)
	v_pk_mul_f32 v[26:27], v[106:107], v[26:27]
	v_pk_mul_f32 v[28:29], v[108:109], v[28:29]
	v_pk_mul_f32 v[18:19], v[110:111], v[18:19]
	v_pk_mul_f32 v[20:21], v[112:113], v[20:21]
	v_lshlrev_b32_e32 v88, 16, v150
	v_and_b32_e32 v150, 0xffff0000, v150
	v_lshlrev_b32_e32 v89, 16, v151
	v_and_b32_e32 v151, 0xffff0000, v151
	v_lshlrev_b32_e32 v90, 16, v152
	v_and_b32_e32 v152, 0xffff0000, v152
	v_lshlrev_b32_e32 v91, 16, v153
	v_and_b32_e32 v153, 0xffff0000, v153
	v_mul_f32_e32 v88, v26, v88
	v_mul_f32_e32 v150, v27, v150
	v_mul_f32_e32 v89, v28, v89
	v_mul_f32_e32 v151, v29, v151
	v_mul_f32_e32 v90, v18, v90
	v_mul_f32_e32 v152, v19, v152
	v_mul_f32_e32 v91, v20, v91
	v_mul_f32_e32 v153, v21, v153
	v_cvt_pk_bf16_f32 v150, v88, v150
	v_cvt_pk_bf16_f32 v151, v89, v151
	v_cvt_pk_bf16_f32 v152, v90, v152
	v_cvt_pk_bf16_f32 v153, v91, v153
	global_store_dwordx4 v[78:79], v[150:153], off offset:16
	s_waitcnt vmcnt(12)
	v_pk_mul_f32 v[30:31], v[114:115], v[30:31]
	v_pk_mul_f32 v[32:33], v[116:117], v[32:33]
	v_pk_mul_f32 v[42:43], v[118:119], v[42:43]
	v_pk_mul_f32 v[44:45], v[120:121], v[44:45]
	v_lshlrev_b32_e32 v88, 16, v154
	v_and_b32_e32 v154, 0xffff0000, v154
	v_lshlrev_b32_e32 v89, 16, v155
	v_and_b32_e32 v155, 0xffff0000, v155
	v_lshlrev_b32_e32 v90, 16, v156
	v_and_b32_e32 v156, 0xffff0000, v156
	v_lshlrev_b32_e32 v91, 16, v157
	v_and_b32_e32 v157, 0xffff0000, v157
	v_mul_f32_e32 v88, v30, v88
	v_mul_f32_e32 v154, v31, v154
	v_mul_f32_e32 v89, v32, v89
	v_mul_f32_e32 v155, v33, v155
	v_mul_f32_e32 v90, v42, v90
	v_mul_f32_e32 v156, v43, v156
	v_mul_f32_e32 v91, v44, v91
	v_mul_f32_e32 v157, v45, v157
	v_cvt_pk_bf16_f32 v154, v88, v154
	v_cvt_pk_bf16_f32 v155, v89, v155
	v_cvt_pk_bf16_f32 v156, v90, v156
	v_cvt_pk_bf16_f32 v157, v91, v157
	global_store_dwordx4 v[78:79], v[154:157], off offset:32
	s_waitcnt vmcnt(11)
	v_pk_mul_f32 v[38:39], v[122:123], v[38:39]
	v_pk_mul_f32 v[40:41], v[124:125], v[40:41]
	v_pk_mul_f32 v[54:55], v[126:127], v[54:55]
	v_pk_mul_f32 v[56:57], v[128:129], v[56:57]
	v_lshlrev_b32_e32 v88, 16, v158
	v_and_b32_e32 v158, 0xffff0000, v158
	v_lshlrev_b32_e32 v89, 16, v159
	v_and_b32_e32 v159, 0xffff0000, v159
	v_lshlrev_b32_e32 v90, 16, v160
	v_and_b32_e32 v160, 0xffff0000, v160
	v_lshlrev_b32_e32 v91, 16, v161
	v_and_b32_e32 v161, 0xffff0000, v161
	v_mul_f32_e32 v88, v38, v88
	v_mul_f32_e32 v158, v39, v158
	v_mul_f32_e32 v89, v40, v89
	v_mul_f32_e32 v159, v41, v159
	v_mul_f32_e32 v90, v54, v90
	v_mul_f32_e32 v160, v55, v160
	v_mul_f32_e32 v91, v56, v91
	v_mul_f32_e32 v161, v57, v161
	v_cvt_pk_bf16_f32 v158, v88, v158
	v_cvt_pk_bf16_f32 v159, v89, v159
	v_cvt_pk_bf16_f32 v160, v90, v160
	v_cvt_pk_bf16_f32 v161, v91, v161
	global_store_dwordx4 v[78:79], v[158:161], off offset:48
	s_waitcnt vmcnt(10)
	v_pk_mul_f32 v[58:59], v[130:131], v[58:59]
	v_pk_mul_f32 v[60:61], v[132:133], v[60:61]
	v_pk_mul_f32 v[62:63], v[134:135], v[62:63]
	v_pk_mul_f32 v[64:65], v[136:137], v[64:65]
	v_lshlrev_b32_e32 v88, 16, v162
	v_and_b32_e32 v162, 0xffff0000, v162
	v_lshlrev_b32_e32 v89, 16, v163
	v_and_b32_e32 v163, 0xffff0000, v163
	v_lshlrev_b32_e32 v90, 16, v164
	v_and_b32_e32 v164, 0xffff0000, v164
	v_lshlrev_b32_e32 v91, 16, v165
	v_and_b32_e32 v165, 0xffff0000, v165
	v_mul_f32_e32 v88, v58, v88
	v_mul_f32_e32 v162, v59, v162
	v_mul_f32_e32 v89, v60, v89
	v_mul_f32_e32 v163, v61, v163
	v_mul_f32_e32 v90, v62, v90
	v_mul_f32_e32 v164, v63, v164
	v_mul_f32_e32 v91, v64, v91
	v_mul_f32_e32 v165, v65, v165
	v_cvt_pk_bf16_f32 v162, v88, v162
	v_cvt_pk_bf16_f32 v163, v89, v163
	v_cvt_pk_bf16_f32 v164, v90, v164
	v_cvt_pk_bf16_f32 v165, v91, v165
	global_store_dwordx4 v[78:79], v[162:165], off offset:64
	s_waitcnt vmcnt(9)
	v_pk_mul_f32 v[34:35], v[138:139], v[34:35]
	v_pk_mul_f32 v[36:37], v[140:141], v[36:37]
	v_pk_mul_f32 v[22:23], v[142:143], v[22:23]
	v_pk_mul_f32 v[24:25], v[144:145], v[24:25]
	v_lshlrev_b32_e32 v88, 16, v166
	v_and_b32_e32 v166, 0xffff0000, v166
	v_lshlrev_b32_e32 v89, 16, v167
	v_and_b32_e32 v167, 0xffff0000, v167
	v_lshlrev_b32_e32 v90, 16, v168
	v_and_b32_e32 v168, 0xffff0000, v168
	v_lshlrev_b32_e32 v91, 16, v169
	v_and_b32_e32 v169, 0xffff0000, v169
	v_mul_f32_e32 v88, v34, v88
	v_mul_f32_e32 v166, v35, v166
	v_mul_f32_e32 v89, v36, v89
	v_mul_f32_e32 v167, v37, v167
	v_mul_f32_e32 v90, v22, v90
	v_mul_f32_e32 v168, v23, v168
	v_mul_f32_e32 v91, v24, v91
	v_mul_f32_e32 v169, v25, v169
	v_cvt_pk_bf16_f32 v166, v88, v166
	v_cvt_pk_bf16_f32 v167, v89, v167
	v_cvt_pk_bf16_f32 v168, v90, v168
	v_cvt_pk_bf16_f32 v169, v91, v169
	global_store_dwordx4 v[78:79], v[166:169], off offset:80
	s_waitcnt vmcnt(8)
	v_pk_mul_f32 v[14:15], v[66:67], v[14:15]
	v_pk_mul_f32 v[16:17], v[68:69], v[16:17]
	v_pk_mul_f32 v[10:11], v[70:71], v[10:11]
	v_pk_mul_f32 v[12:13], v[72:73], v[12:13]
	v_lshlrev_b32_e32 v88, 16, v170
	v_and_b32_e32 v170, 0xffff0000, v170
	v_lshlrev_b32_e32 v89, 16, v171
	v_and_b32_e32 v171, 0xffff0000, v171
	v_lshlrev_b32_e32 v90, 16, v172
	v_and_b32_e32 v172, 0xffff0000, v172
	v_lshlrev_b32_e32 v91, 16, v173
	v_and_b32_e32 v173, 0xffff0000, v173
	v_mul_f32_e32 v88, v14, v88
	v_mul_f32_e32 v170, v15, v170
	v_mul_f32_e32 v89, v16, v89
	v_mul_f32_e32 v171, v17, v171
	v_mul_f32_e32 v90, v10, v90
	v_mul_f32_e32 v172, v11, v172
	v_mul_f32_e32 v91, v12, v91
	v_mul_f32_e32 v173, v13, v173
	v_cvt_pk_bf16_f32 v170, v88, v170
	v_cvt_pk_bf16_f32 v171, v89, v171
	v_cvt_pk_bf16_f32 v172, v90, v172
	v_cvt_pk_bf16_f32 v173, v91, v173
	global_store_dwordx4 v[78:79], v[170:173], off offset:96
	s_waitcnt vmcnt(7)
	v_pk_mul_f32 v[6:7], v[74:75], v[6:7]
	v_pk_mul_f32 v[8:9], v[76:77], v[8:9]
	v_pk_mul_f32 v[2:3], v[84:85], v[2:3]
	v_pk_mul_f32 v[4:5], v[86:87], v[4:5]
	v_lshlrev_b32_e32 v88, 16, v174
	v_and_b32_e32 v174, 0xffff0000, v174
	v_lshlrev_b32_e32 v89, 16, v175
	v_and_b32_e32 v175, 0xffff0000, v175
	v_lshlrev_b32_e32 v90, 16, v176
	v_and_b32_e32 v176, 0xffff0000, v176
	v_lshlrev_b32_e32 v91, 16, v177
	v_and_b32_e32 v177, 0xffff0000, v177
	v_mul_f32_e32 v88, v6, v88
	v_mul_f32_e32 v174, v7, v174
	v_mul_f32_e32 v89, v8, v89
	v_mul_f32_e32 v175, v9, v175
	v_mul_f32_e32 v90, v2, v90
	v_mul_f32_e32 v176, v3, v176
	v_mul_f32_e32 v91, v4, v91
	v_mul_f32_e32 v177, v5, v177
	v_cvt_pk_bf16_f32 v174, v88, v174
	v_cvt_pk_bf16_f32 v175, v89, v175
	v_cvt_pk_bf16_f32 v176, v90, v176
	v_cvt_pk_bf16_f32 v177, v91, v177
	global_store_dwordx4 v[78:79], v[174:177], off offset:112
	s_branch .LBB0_266
